# emission waves sleep 384 cycles at the start of step 5 so the solve waves' column loads enter the LDS queue ahead of the emission's bank-conflicted reads
# speedup vs baseline: 1.0017x; 1.0013x over previous
.LBB0_203:
	s_cmp_gt_i32 s48, 3
	s_mov_b64 s[28:29], -1
	s_waitcnt lgkmcnt(0)
	s_barrier
	s_cbranch_scc0 .LBB0_216
	s_sleep 6
	s_andn2_b64 vcc, exec, s[94:95]
	s_cbranch_vccnz .LBB0_206
	s_waitcnt vmcnt(2)
